# f32 divisions in scan staging (sigmoid/tanh/normalise) and merge sigmoid use v_rcp_f32 + mul instead of the IEEE division expansion; dead chain instructions removed with hazard distances preserved
# speedup vs baseline: 1.0820x; 1.0145x over previous
.LBB0_644:
	ds_read_b128 v[78:81], v180
	ds_read_b128 v[82:85], v180 offset:16
	s_waitcnt vmcnt(5)
	v_lshlrev_b32_e32 v88, 16, v22
	v_and_b32_e32 v89, 0xffff0000, v22
	v_lshlrev_b32_e32 v90, 16, v26
	v_and_b32_e32 v91, 0xffff0000, v26
	v_lshlrev_b32_e32 v86, 16, v18
	v_and_b32_e32 v87, 0xffff0000, v18
	v_pk_add_f32 v[88:89], v[88:89], v[90:91]
	v_lshlrev_b32_e32 v90, 16, v27
	v_pk_fma_f32 v[88:89], v[88:89], 0.5, v[86:87] op_sel_hi:[1,0,1] neg_lo:[0,0,1] neg_hi:[0,0,1]
	v_and_b32_e32 v91, 0xffff0000, v27
	s_waitcnt lgkmcnt(1)
	v_pk_fma_f32 v[78:79], v[88:89], v[78:79], v[86:87]
	v_lshlrev_b32_e32 v88, 16, v23
	v_and_b32_e32 v89, 0xffff0000, v23
	v_lshlrev_b32_e32 v86, 16, v19
	v_and_b32_e32 v87, 0xffff0000, v19
	v_pk_add_f32 v[88:89], v[88:89], v[90:91]
	s_waitcnt vmcnt(4)
	v_lshlrev_b32_e32 v90, 16, v39
	v_pk_fma_f32 v[88:89], v[88:89], 0.5, v[86:87] op_sel_hi:[1,0,1] neg_lo:[0,0,1] neg_hi:[0,0,1]
	v_and_b32_e32 v91, 0xffff0000, v39
	v_pk_fma_f32 v[80:81], v[88:89], v[80:81], v[86:87]
	ds_write_b128 v181, v[78:81]
	v_lshlrev_b32_e32 v80, 16, v24
	v_and_b32_e32 v81, 0xffff0000, v24
	v_lshlrev_b32_e32 v86, 16, v28
	v_and_b32_e32 v87, 0xffff0000, v28
	v_lshlrev_b32_e32 v78, 16, v20
	v_and_b32_e32 v79, 0xffff0000, v20
	v_pk_add_f32 v[80:81], v[80:81], v[86:87]
	v_lshlrev_b32_e32 v86, 16, v29
	v_pk_fma_f32 v[80:81], v[80:81], 0.5, v[78:79] op_sel_hi:[1,0,1] neg_lo:[0,0,1] neg_hi:[0,0,1]
	v_and_b32_e32 v87, 0xffff0000, v29
	s_waitcnt lgkmcnt(1)
	v_pk_fma_f32 v[78:79], v[80:81], v[82:83], v[78:79]
	v_lshlrev_b32_e32 v82, 16, v25
	v_and_b32_e32 v83, 0xffff0000, v25
	v_lshlrev_b32_e32 v80, 16, v21
	v_and_b32_e32 v81, 0xffff0000, v21
	v_pk_add_f32 v[82:83], v[82:83], v[86:87]
	v_lshlrev_b32_e32 v86, 16, v30
	v_pk_fma_f32 v[82:83], v[82:83], 0.5, v[80:81] op_sel_hi:[1,0,1] neg_lo:[0,0,1] neg_hi:[0,0,1]
	v_and_b32_e32 v87, 0xffff0000, v30
	v_pk_fma_f32 v[80:81], v[82:83], v[84:85], v[80:81]
	ds_write_b128 v181, v[78:81] offset:16
	ds_read_b128 v[78:81], v182
	v_lshlrev_b32_e32 v82, 16, v34
	v_and_b32_e32 v83, 0xffff0000, v34
	v_lshlrev_b32_e32 v84, 16, v38
	v_and_b32_e32 v85, 0xffff0000, v38
	v_pk_add_f32 v[82:83], v[82:83], v[84:85]
	s_waitcnt vmcnt(3)
	v_lshlrev_b32_e32 v98, 16, v47
	v_pk_fma_f32 v[88:89], v[82:83], 0.5, v[86:87] op_sel_hi:[1,0,1] neg_lo:[0,0,1] neg_hi:[0,0,1]
	ds_read_b128 v[82:85], v182 offset:16
	s_waitcnt lgkmcnt(1)
	v_pk_fma_f32 v[78:79], v[88:89], v[78:79], v[86:87]
	v_lshlrev_b32_e32 v88, 16, v35
	v_and_b32_e32 v89, 0xffff0000, v35
	v_lshlrev_b32_e32 v86, 16, v31
	v_and_b32_e32 v87, 0xffff0000, v31
	v_pk_add_f32 v[88:89], v[88:89], v[90:91]
	v_lshlrev_b32_e32 v90, 16, v42
	v_pk_fma_f32 v[88:89], v[88:89], 0.5, v[86:87] op_sel_hi:[1,0,1] neg_lo:[0,0,1] neg_hi:[0,0,1]
	v_and_b32_e32 v91, 0xffff0000, v42
	v_pk_fma_f32 v[80:81], v[88:89], v[80:81], v[86:87]
	ds_write_b128 v181, v[78:81] offset:8192
	v_lshlrev_b32_e32 v80, 16, v36
	v_and_b32_e32 v81, 0xffff0000, v36
	v_lshlrev_b32_e32 v86, 16, v40
	v_and_b32_e32 v87, 0xffff0000, v40
	v_lshlrev_b32_e32 v78, 16, v32
	v_and_b32_e32 v79, 0xffff0000, v32
	v_pk_add_f32 v[80:81], v[80:81], v[86:87]
	v_lshlrev_b32_e32 v86, 16, v41
	v_pk_fma_f32 v[80:81], v[80:81], 0.5, v[78:79] op_sel_hi:[1,0,1] neg_lo:[0,0,1] neg_hi:[0,0,1]
	v_and_b32_e32 v87, 0xffff0000, v41
	s_waitcnt lgkmcnt(1)
	v_pk_fma_f32 v[78:79], v[80:81], v[82:83], v[78:79]
	v_lshlrev_b32_e32 v82, 16, v37
	v_and_b32_e32 v83, 0xffff0000, v37
	v_lshlrev_b32_e32 v80, 16, v33
	v_and_b32_e32 v81, 0xffff0000, v33
	v_pk_add_f32 v[82:83], v[82:83], v[86:87]
	v_and_b32_e32 v99, 0xffff0000, v47
	v_pk_fma_f32 v[82:83], v[82:83], 0.5, v[80:81] op_sel_hi:[1,0,1] neg_lo:[0,0,1] neg_hi:[0,0,1]
	v_lshlrev_b32_e32 v100, 16, v51
	v_pk_fma_f32 v[80:81], v[82:83], v[84:85], v[80:81]
	ds_write_b128 v181, v[78:81] offset:8208
	ds_read_b128 v[78:81], v183
	v_lshlrev_b32_e32 v82, 16, v46
	v_and_b32_e32 v83, 0xffff0000, v46
	v_lshlrev_b32_e32 v84, 16, v50
	v_and_b32_e32 v85, 0xffff0000, v50
	v_pk_add_f32 v[86:87], v[82:83], v[84:85]
	ds_read_b128 v[82:85], v184
	v_pk_fma_f32 v[92:93], v[86:87], 0.5, v[90:91] op_sel_hi:[1,0,1] neg_lo:[0,0,1] neg_hi:[0,0,1]
	ds_read_b128 v[86:89], v183 offset:16
	s_waitcnt lgkmcnt(2)
	v_pk_fma_f32 v[78:79], v[92:93], v[78:79], v[90:91]
	v_and_b32_e32 v101, 0xffff0000, v51
	ds_read_b128 v[90:93], v184 offset:16
	s_waitcnt lgkmcnt(2)
	v_pk_mul_f32 v[94:95], v[78:79], v[82:83]
	v_lshlrev_b32_e32 v82, 16, v43
	v_and_b32_e32 v83, 0xffff0000, v43
	v_pk_add_f32 v[98:99], v[98:99], v[100:101]
	v_lshlrev_b32_e32 v102, 16, v52
	v_pk_fma_f32 v[98:99], v[98:99], 0.5, v[82:83] op_sel_hi:[1,0,1] neg_lo:[0,0,1] neg_hi:[0,0,1]
	v_and_b32_e32 v103, 0xffff0000, v52
	v_pk_fma_f32 v[80:81], v[98:99], v[80:81], v[82:83]
	v_lshlrev_b32_e32 v82, 16, v44
	v_pk_mul_f32 v[98:99], v[80:81], v[84:85]
	v_lshlrev_b32_e32 v84, 16, v48
	v_and_b32_e32 v85, 0xffff0000, v48
	v_and_b32_e32 v83, 0xffff0000, v44
	v_pk_add_f32 v[84:85], v[84:85], v[102:103]
	v_pk_mul_f32 v[96:97], v[94:95], v[94:95]
	v_pk_fma_f32 v[84:85], v[84:85], 0.5, v[82:83] op_sel_hi:[1,0,1] neg_lo:[0,0,1] neg_hi:[0,0,1]
	v_lshlrev_b32_e32 v102, 16, v49
	v_and_b32_e32 v103, 0xffff0000, v49
	v_lshlrev_b32_e32 v104, 16, v53
	v_and_b32_e32 v105, 0xffff0000, v53
	v_pk_mul_f32 v[100:101], v[98:99], v[98:99]
	s_waitcnt lgkmcnt(1)
	v_pk_fma_f32 v[82:83], v[84:85], v[86:87], v[82:83]
	v_lshlrev_b32_e32 v84, 16, v45
	v_and_b32_e32 v85, 0xffff0000, v45
	v_pk_add_f32 v[102:103], v[102:103], v[104:105]
	v_add_f32_e32 v1, v96, v97
	s_waitcnt lgkmcnt(0)
	v_pk_mul_f32 v[86:87], v[82:83], v[90:91]
	v_pk_fma_f32 v[102:103], v[102:103], 0.5, v[84:85] op_sel_hi:[1,0,1] neg_lo:[0,0,1] neg_hi:[0,0,1]
	v_add_f32_e32 v1, v1, v100
	v_pk_mul_f32 v[90:91], v[86:87], v[86:87]
	v_pk_fma_f32 v[84:85], v[102:103], v[88:89], v[84:85]
	v_add_f32_e32 v1, v1, v101
	v_pk_mul_f32 v[88:89], v[84:85], v[92:93]
	v_add_f32_e32 v1, v1, v90
	v_pk_mul_f32 v[92:93], v[88:89], v[88:89]
	v_add_f32_e32 v1, v1, v91
	v_add_f32_e32 v1, v1, v92
	v_add_f32_e32 v1, v1, v93
	s_mov_b32 s6, 0xf800000
	ds_write_b128 v181, v[78:81] offset:24576
	ds_write_b128 v181, v[82:85] offset:24592
	v_add_f32_dpp v1, v1, v1 quad_perm:[1,0,3,2] row_mask:0xf bank_mask:0xf bound_ctrl:1
	s_nop 1
	v_add_f32_dpp v1, v1, v1 quad_perm:[2,3,0,1] row_mask:0xf bank_mask:0xf bound_ctrl:1
	s_nop 1
	v_add_f32_dpp v1, v1, v1 row_half_mirror row_mask:0xf bank_mask:0xf bound_ctrl:1
	v_mul_f32_e32 v90, 0x4f800000, v1
	v_cmp_gt_f32_e32 vcc, s6, v1
	s_nop 1
	v_cndmask_b32_e32 v1, v1, v90, vcc
	v_sqrt_f32_e32 v90, v1
	s_nop 0
	v_add_u32_e32 v91, -1, v90
	v_fma_f32 v92, -v91, v90, v1
	v_cmp_ge_f32_e64 s[46:47], 0, v92
	v_add_u32_e32 v92, 1, v90
	s_nop 0
	v_cndmask_b32_e64 v91, v90, v91, s[46:47]
	v_fma_f32 v90, -v92, v90, v1
	v_cmp_lt_f32_e64 s[46:47], 0, v90
	s_nop 1
	v_cndmask_b32_e64 v90, v91, v92, s[46:47]
	v_mul_f32_e32 v91, 0x37800000, v90
	v_cndmask_b32_e32 v90, v90, v91, vcc
	v_cmp_class_f32_e32 vcc, v1, v237
	s_waitcnt vmcnt(2)
	v_and_b32_e32 v92, 0xffff0000, v57
	v_cndmask_b32_e32 v1, v90, v1, vcc
	v_max_f32_e32 v1, 0x2b8cbccc, v1
	s_nop 0
	v_rcp_f32_e32 v82, v1
	s_nop 0
	v_pk_mul_f32 v[78:79], v[94:95], v[82:83] op_sel_hi:[1,0]
	v_pk_mul_f32 v[80:81], v[98:99], v[82:83] op_sel_hi:[1,0]
	ds_write_b128 v181, v[78:81] offset:16384
	v_pk_mul_f32 v[78:79], v[86:87], v[82:83] op_sel_hi:[1,0]
	v_pk_mul_f32 v[80:81], v[88:89], v[82:83] op_sel_hi:[1,0]
	ds_write_b128 v181, v[78:81] offset:16400
	ds_read_b128 v[78:81], v185
	ds_read_b128 v[82:85], v185 offset:16
	v_lshlrev_b32_e32 v87, 16, v58
	v_lshlrev_b32_e32 v88, 16, v62
	v_lshlrev_b32_e32 v1, 16, v54
	v_add_f32_e32 v87, v88, v87
	v_fma_f32 v87, v87, 0.5, -v1
	s_waitcnt lgkmcnt(1)
	v_fmac_f32_e32 v1, v87, v78
	v_and_b32_e32 v78, 0xffff0000, v62
	v_and_b32_e32 v87, 0xffff0000, v58
	v_and_b32_e32 v86, 0xffff0000, v54
	v_add_f32_e32 v78, v78, v87
	v_fma_f32 v78, v78, 0.5, -v86
	v_fmac_f32_e32 v86, v78, v79
	v_lshlrev_b32_e32 v78, 16, v59
	v_lshlrev_b32_e32 v79, 16, v63
	v_lshlrev_b32_e32 v87, 16, v55
	v_add_f32_e32 v78, v79, v78
	v_fma_f32 v78, v78, 0.5, -v87
	v_fmac_f32_e32 v87, v78, v80
	v_and_b32_e32 v78, 0xffff0000, v63
	v_and_b32_e32 v79, 0xffff0000, v59
	v_and_b32_e32 v88, 0xffff0000, v55
	v_add_f32_e32 v78, v78, v79
	v_fma_f32 v78, v78, 0.5, -v88
	v_fmac_f32_e32 v88, v78, v81
	v_lshlrev_b32_e32 v78, 16, v60
	v_lshlrev_b32_e32 v79, 16, v64
	v_lshlrev_b32_e32 v89, 16, v56
	v_add_f32_e32 v78, v79, v78
	v_fma_f32 v78, v78, 0.5, -v89
	s_waitcnt lgkmcnt(0)
	v_fmac_f32_e32 v89, v78, v82
	v_and_b32_e32 v78, 0xffff0000, v64
	v_and_b32_e32 v79, 0xffff0000, v60
	v_and_b32_e32 v90, 0xffff0000, v56
	v_add_f32_e32 v78, v78, v79
	v_fma_f32 v78, v78, 0.5, -v90
	v_fmac_f32_e32 v90, v78, v83
	v_lshlrev_b32_e32 v78, 16, v61
	v_lshlrev_b32_e32 v79, 16, v65
	v_add_f32_e32 v1, v1, v1
	v_lshlrev_b32_e32 v91, 16, v57
	v_add_f32_e32 v78, v79, v78
	v_mul_f32_e32 v1, 0x3fb8aa3b, v1
	v_fma_f32 v80, v78, 0.5, -v91
	v_exp_f32_e32 v78, v1
	v_add_f32_e32 v1, v86, v86
	v_mul_f32_e32 v1, 0x3fb8aa3b, v1
	v_exp_f32_e32 v79, v1
	v_fmac_f32_e32 v91, v80, v84
	v_and_b32_e32 v1, 0xffff0000, v65
	v_and_b32_e32 v80, 0xffff0000, v61
	v_pk_add_f32 v[78:79], v[78:79], 1.0 op_sel_hi:[1,0]
	v_add_f32_e32 v1, v1, v80
	v_fma_f32 v1, v1, 0.5, -v92
	v_fmac_f32_e32 v92, v1, v85
	v_add_f32_e32 v80, v87, v87
	v_add_f32_e32 v81, v88, v88
	v_mul_f32_e32 v80, 0x3fb8aa3b, v80
	v_mul_f32_e32 v81, 0x3fb8aa3b, v81
	v_rcp_f32_e32 v1, v79
	s_nop 0
	v_mul_f32_e32 v79, 2.0, v1
	v_exp_f32_e32 v80, v80
	v_exp_f32_e32 v81, v81
	s_nop 4
	v_pk_add_f32 v[80:81], v[80:81], 1.0 op_sel_hi:[1,0]
	v_rcp_f32_e32 v1, v78
	s_nop 0
	v_mul_f32_e32 v78, 2.0, v1
	v_pk_add_f32 v[78:79], v[78:79], 1.0 op_sel_hi:[1,0] neg_lo:[1,0] neg_hi:[1,0]
	v_add_f32_e32 v82, v89, v89
	v_add_f32_e32 v83, v90, v90
	v_mul_f32_e32 v82, 0x3fb8aa3b, v82
	v_mul_f32_e32 v83, 0x3fb8aa3b, v83
	v_rcp_f32_e32 v1, v81
	s_nop 0
	v_mul_f32_e32 v81, 2.0, v1
	v_exp_f32_e32 v82, v82
	v_exp_f32_e32 v83, v83
	s_nop 4
	v_pk_add_f32 v[82:83], v[82:83], 1.0 op_sel_hi:[1,0]
	v_rcp_f32_e32 v1, v80
	s_nop 0
	v_mul_f32_e32 v80, 2.0, v1
	v_pk_add_f32 v[80:81], v[80:81], 1.0 op_sel_hi:[1,0] neg_lo:[1,0] neg_hi:[1,0]
	v_add_f32_e32 v84, v91, v91
	v_add_f32_e32 v85, v92, v92
	v_mul_f32_e32 v84, 0x3fb8aa3b, v84
	v_mul_f32_e32 v85, 0x3fb8aa3b, v85
	v_rcp_f32_e32 v1, v83
	s_nop 0
	v_mul_f32_e32 v83, 2.0, v1
	v_exp_f32_e32 v84, v84
	v_exp_f32_e32 v85, v85
	s_nop 4
	v_pk_add_f32 v[84:85], v[84:85], 1.0 op_sel_hi:[1,0]
	v_rcp_f32_e32 v1, v82
	s_nop 0
	v_mul_f32_e32 v82, 2.0, v1
	v_pk_add_f32 v[82:83], v[82:83], 1.0 op_sel_hi:[1,0] neg_lo:[1,0] neg_hi:[1,0]
	v_rcp_f32_e32 v1, v85
	s_nop 0
	v_mul_f32_e32 v85, 2.0, v1
	v_cvt_pk_bf16_f32 v78, v78, v79
	v_rcp_f32_e32 v1, v84
	s_nop 0
	v_mul_f32_e32 v84, 2.0, v1
	v_pk_add_f32 v[84:85], v[84:85], 1.0 op_sel_hi:[1,0] neg_lo:[1,0] neg_hi:[1,0]
	v_cvt_pk_bf16_f32 v79, v80, v81
	v_cvt_pk_bf16_f32 v80, v82, v83
	v_cvt_pk_bf16_f32 v81, v84, v85
	ds_write_b128 v186, v[78:81] offset:57856
	ds_read_b128 v[78:81], v187
	ds_read_b128 v[82:85], v187 offset:16
	s_waitcnt vmcnt(1)
	v_lshlrev_b32_e32 v88, 16, v70
	v_and_b32_e32 v89, 0xffff0000, v70
	v_lshlrev_b32_e32 v90, 16, v74
	v_and_b32_e32 v91, 0xffff0000, v74
	v_lshlrev_b32_e32 v86, 16, v66
	v_and_b32_e32 v87, 0xffff0000, v66
	v_pk_add_f32 v[88:89], v[88:89], v[90:91]
	v_lshlrev_b32_e32 v90, 16, v75
	v_pk_fma_f32 v[88:89], v[88:89], 0.5, v[86:87] op_sel_hi:[1,0,1] neg_lo:[0,0,1] neg_hi:[0,0,1]
	v_and_b32_e32 v91, 0xffff0000, v75
	s_waitcnt lgkmcnt(1)
	v_pk_fma_f32 v[78:79], v[88:89], v[78:79], v[86:87]
	v_lshlrev_b32_e32 v88, 16, v71
	v_and_b32_e32 v89, 0xffff0000, v71
	v_lshlrev_b32_e32 v86, 16, v67
	v_and_b32_e32 v87, 0xffff0000, v67
	v_pk_add_f32 v[88:89], v[88:89], v[90:91]
	v_lshlrev_b32_e32 v90, 16, v76
	v_pk_fma_f32 v[88:89], v[88:89], 0.5, v[86:87] op_sel_hi:[1,0,1] neg_lo:[0,0,1] neg_hi:[0,0,1]
	v_and_b32_e32 v91, 0xffff0000, v76
	v_pk_fma_f32 v[80:81], v[88:89], v[80:81], v[86:87]
	v_lshlrev_b32_e32 v88, 16, v72
	v_and_b32_e32 v89, 0xffff0000, v72
	v_lshlrev_b32_e32 v86, 16, v68
	v_and_b32_e32 v87, 0xffff0000, v68
	v_pk_add_f32 v[88:89], v[88:89], v[90:91]
	v_lshlrev_b32_e32 v90, 16, v77
	v_pk_fma_f32 v[88:89], v[88:89], 0.5, v[86:87] op_sel_hi:[1,0,1] neg_lo:[0,0,1] neg_hi:[0,0,1]
	v_and_b32_e32 v91, 0xffff0000, v77
	s_waitcnt lgkmcnt(0)
	v_pk_fma_f32 v[82:83], v[88:89], v[82:83], v[86:87]
	v_lshlrev_b32_e32 v88, 16, v73
	v_and_b32_e32 v89, 0xffff0000, v73
	v_lshlrev_b32_e32 v86, 16, v69
	v_and_b32_e32 v87, 0xffff0000, v69
	v_pk_add_f32 v[88:89], v[88:89], v[90:91]
	v_cvt_pk_bf16_f32 v78, v78, v79
	v_pk_fma_f32 v[88:89], v[88:89], 0.5, v[86:87] op_sel_hi:[1,0,1] neg_lo:[0,0,1] neg_hi:[0,0,1]
	v_cvt_pk_bf16_f32 v79, v80, v81
	v_pk_fma_f32 v[84:85], v[88:89], v[84:85], v[86:87]
	v_cvt_pk_bf16_f32 v80, v82, v83
	v_cvt_pk_bf16_f32 v81, v84, v85
	ds_write_b128 v186, v[78:81] offset:62464
	s_waitcnt lgkmcnt(0)
	s_barrier
	ds_read_b128 v[78:81], v159 offset:57856
	ds_read_b128 v[82:85], v159 offset:57920
	s_waitcnt lgkmcnt(1)
	v_mfma_f32_16x16x32_bf16 v[78:81], v[78:81], v[2:5], 0
	ds_read_b128 v[86:89], v159 offset:62464
	s_waitcnt lgkmcnt(1)
	v_mfma_f32_16x16x32_bf16 v[82:85], v[82:85], v[6:9], v[78:81]
	s_nop 4
	ds_read_b128 v[78:81], v159 offset:62528
	s_waitcnt lgkmcnt(1)
	v_mfma_f32_16x16x32_bf16 v[86:89], v[86:89], v[10:13], 0
	v_add_f32_e32 v1, v173, v82
	v_mul_f32_e32 v1, 0xbfb8aa3b, v1
	v_exp_f32_e32 v1, v1
	s_waitcnt lgkmcnt(0)
	v_mfma_f32_16x16x32_bf16 v[78:81], v[78:81], v[14:17], v[86:89]
	v_add_f32_e32 v1, 1.0, v1
	s_nop 4
	s_nop 1
	v_add_f32_e32 v78, v175, v78
	v_mul_f32_e32 v78, 0xbfb8aa3b, v78
	v_exp_f32_e32 v78, v78
	s_nop 5
	v_add_f32_e32 v78, 1.0, v78
	v_rcp_f32_e32 v82, v1
	s_nop 0
	v_mul_f32_e32 v1, s16, v82
	v_mul_f32_e32 v1, 0x3fb8aa3b, v1
	ds_read2st64_b32 v[86:87], v193 offset1:64
	v_rcp_f32_e32 v78, v78
	s_nop 0
	ds_read_b32 v82, v193 offset:24576
	s_nop 0
	v_exp_f32_e32 v1, v1
	s_waitcnt lgkmcnt(1)
	v_mul_f32_e32 v87, v87, v78
	v_add_f32_e32 v78, -1.0, v78
	v_fma_f32 v78, v176, v78, 1.0
	s_waitcnt lgkmcnt(0)
	v_mul_f32_e32 v78, v82, v78
	ds_write2st64_b32 v193, v78, v1 offset0:96 offset1:128
	v_mul_f32_e32 v1, v86, v78
	v_mul_f32_e32 v78, v177, v1
	ds_write_b32 v193, v87 offset:40960
	s_nop 0
	v_mov_b32_dpp v78, v78 quad_perm:[1,0,3,2] row_mask:0xf bank_mask:0xf bound_ctrl:1
	v_fmac_f32_e32 v78, v177, v1
	s_nop 1
	v_add_f32_dpp v1, v78, v78 quad_perm:[2,3,0,1] row_mask:0xf bank_mask:0xf bound_ctrl:1
	s_nop 1
	v_add_f32_dpp v1, v1, v1 row_half_mirror row_mask:0xf bank_mask:0xf bound_ctrl:1
	s_nop 1
	v_mov_b32_dpp v78, v1 row_mirror row_mask:0xf bank_mask:0xf bound_ctrl:1
	s_and_saveexec_b64 s[6:7], s[40:41]
	v_add_f32_e32 v1, v1, v78
	ds_write_b32 v194, v1 offset:57344
	s_or_b64 exec, exec, s[6:7]
	v_add_f32_e32 v1, v173, v83
	v_mul_f32_e32 v1, 0xbfb8aa3b, v1
	v_exp_f32_e32 v1, v1
	v_add_f32_e32 v78, v175, v79
	v_mul_f32_e32 v78, 0xbfb8aa3b, v78
	v_exp_f32_e32 v78, v78
	v_add_f32_e32 v1, 1.0, v1
	s_nop 3
	v_add_f32_e32 v82, 1.0, v78
	v_rcp_f32_e32 v79, v1
	s_nop 0
	v_mul_f32_e32 v1, s16, v79
	v_mul_f32_e32 v1, 0x3fb8aa3b, v1
	v_exp_f32_e32 v1, v1
	ds_read2st64_b32 v[78:79], v195 offset1:64
	v_rcp_f32_e32 v82, v82
	s_nop 0
	ds_read_b32 v83, v195 offset:24576
	s_waitcnt lgkmcnt(1)
	v_mul_f32_e32 v79, v82, v79
	ds_write_b32 v195, v79 offset:40960
	v_add_f32_e32 v79, -1.0, v82
	v_fma_f32 v79, v176, v79, 1.0
	s_waitcnt lgkmcnt(1)
	v_mul_f32_e32 v79, v79, v83
	ds_write2st64_b32 v195, v79, v1 offset0:96 offset1:128
	v_mul_f32_e32 v1, v79, v78
	v_mul_f32_e32 v78, v177, v1
	s_nop 1
	v_mov_b32_dpp v78, v78 quad_perm:[1,0,3,2] row_mask:0xf bank_mask:0xf bound_ctrl:1
	v_fmac_f32_e32 v78, v177, v1
	s_nop 1
	v_add_f32_dpp v1, v78, v78 quad_perm:[2,3,0,1] row_mask:0xf bank_mask:0xf bound_ctrl:1
	s_nop 1
	v_add_f32_dpp v1, v1, v1 row_half_mirror row_mask:0xf bank_mask:0xf bound_ctrl:1
	s_nop 1
	v_mov_b32_dpp v78, v1 row_mirror row_mask:0xf bank_mask:0xf bound_ctrl:1
	s_and_saveexec_b64 s[6:7], s[40:41]
	v_add_f32_e32 v1, v1, v78
	ds_write_b32 v194, v1 offset:57348
	s_or_b64 exec, exec, s[6:7]
	v_add_f32_e32 v1, v173, v84
	v_mul_f32_e32 v1, 0xbfb8aa3b, v1
	v_exp_f32_e32 v1, v1
	v_add_f32_e32 v78, v175, v80
	v_mul_f32_e32 v78, 0xbfb8aa3b, v78
	v_exp_f32_e32 v78, v78
	v_add_f32_e32 v1, 1.0, v1
	s_nop 3
	v_add_f32_e32 v80, 1.0, v78
	v_rcp_f32_e32 v79, v1
	s_nop 0
	v_mul_f32_e32 v1, s16, v79
	v_mul_f32_e32 v1, 0x3fb8aa3b, v1
	v_exp_f32_e32 v1, v1
	ds_read2st64_b32 v[78:79], v196 offset1:64
	v_rcp_f32_e32 v80, v80
	s_nop 0
	ds_read_b32 v82, v196 offset:24576
	s_waitcnt lgkmcnt(1)
	v_mul_f32_e32 v79, v80, v79
	ds_write_b32 v196, v79 offset:40960
	v_add_f32_e32 v79, -1.0, v80
	v_fma_f32 v79, v176, v79, 1.0
	s_waitcnt lgkmcnt(1)
	v_mul_f32_e32 v79, v79, v82
	ds_write2st64_b32 v196, v79, v1 offset0:96 offset1:128
	v_mul_f32_e32 v1, v79, v78
	v_mul_f32_e32 v78, v177, v1
	s_nop 1
	v_mov_b32_dpp v78, v78 quad_perm:[1,0,3,2] row_mask:0xf bank_mask:0xf bound_ctrl:1
	v_fmac_f32_e32 v78, v177, v1
	s_nop 1
	v_add_f32_dpp v1, v78, v78 quad_perm:[2,3,0,1] row_mask:0xf bank_mask:0xf bound_ctrl:1
	s_nop 1
	v_add_f32_dpp v1, v1, v1 row_half_mirror row_mask:0xf bank_mask:0xf bound_ctrl:1
	s_nop 1
	v_mov_b32_dpp v78, v1 row_mirror row_mask:0xf bank_mask:0xf bound_ctrl:1
	s_and_saveexec_b64 s[6:7], s[40:41]
	v_add_f32_e32 v1, v1, v78
	ds_write_b32 v194, v1 offset:57352
	s_or_b64 exec, exec, s[6:7]
	v_add_f32_e32 v1, v173, v85
	v_mul_f32_e32 v1, 0xbfb8aa3b, v1
	v_exp_f32_e32 v1, v1
	v_add_f32_e32 v78, v175, v81
	v_mul_f32_e32 v78, 0xbfb8aa3b, v78
	v_exp_f32_e32 v78, v78
	v_add_f32_e32 v1, 1.0, v1
	s_nop 3
	v_add_f32_e32 v80, 1.0, v78
	v_rcp_f32_e32 v79, v1
	s_nop 0
	v_mul_f32_e32 v1, s16, v79
	v_mul_f32_e32 v1, 0x3fb8aa3b, v1
	v_exp_f32_e32 v1, v1
	ds_read2st64_b32 v[78:79], v197 offset1:64
	v_rcp_f32_e32 v80, v80
	s_nop 0
	ds_read_b32 v81, v197 offset:24576
	s_waitcnt lgkmcnt(1)
	v_mul_f32_e32 v79, v80, v79
	ds_write_b32 v197, v79 offset:40960
	v_add_f32_e32 v79, -1.0, v80
	v_fma_f32 v79, v176, v79, 1.0
	s_waitcnt lgkmcnt(1)
	v_mul_f32_e32 v79, v79, v81
	ds_write2st64_b32 v197, v79, v1 offset0:96 offset1:128
	v_mul_f32_e32 v1, v79, v78
	v_mul_f32_e32 v78, v177, v1
	s_nop 1
	v_mov_b32_dpp v78, v78 quad_perm:[1,0,3,2] row_mask:0xf bank_mask:0xf bound_ctrl:1
	v_fmac_f32_e32 v78, v177, v1
	s_nop 1
	v_add_f32_dpp v1, v78, v78 quad_perm:[2,3,0,1] row_mask:0xf bank_mask:0xf bound_ctrl:1
	s_nop 1
	v_add_f32_dpp v1, v1, v1 row_half_mirror row_mask:0xf bank_mask:0xf bound_ctrl:1
	s_nop 1
	v_mov_b32_dpp v78, v1 row_mirror row_mask:0xf bank_mask:0xf bound_ctrl:1
	s_and_saveexec_b64 s[6:7], s[40:41]
	v_add_f32_e32 v1, v1, v78
	ds_write_b32 v194, v1 offset:57356
	s_or_b64 exec, exec, s[6:7]
	ds_read_b128 v[82:85], v159 offset:64768
	ds_read_b128 v[78:81], v159 offset:60160
	s_waitcnt lgkmcnt(1)
	v_mfma_f32_16x16x32_bf16 v[86:89], v[82:85], v[10:13], 0
	ds_read_b128 v[82:85], v159 offset:60224
	s_waitcnt lgkmcnt(1)
	v_mfma_f32_16x16x32_bf16 v[78:81], v[78:81], v[2:5], 0
	s_waitcnt lgkmcnt(0)
	v_mfma_f32_16x16x32_bf16 v[82:85], v[82:85], v[6:9], v[78:81]
	s_nop 5
	ds_read_b128 v[78:81], v159 offset:64832
	s_nop 0
	v_add_f32_e32 v1, v173, v82
	v_mul_f32_e32 v1, 0xbfb8aa3b, v1
	v_exp_f32_e32 v1, v1
	s_waitcnt lgkmcnt(0)
	v_mfma_f32_16x16x32_bf16 v[78:81], v[78:81], v[14:17], v[86:89]
	v_add_f32_e32 v1, 1.0, v1
	s_nop 5
	s_nop 0
	v_add_f32_e32 v78, v175, v78
	v_mul_f32_e32 v78, 0xbfb8aa3b, v78
	v_exp_f32_e32 v78, v78
	s_nop 1
	v_add_f32_e32 v78, 1.0, v78
	v_rcp_f32_e32 v82, v1
	s_nop 0
	v_mul_f32_e32 v1, s16, v82
	ds_read2st64_b32 v[86:87], v198 offset1:64
	v_rcp_f32_e32 v78, v78
	s_nop 0
	s_nop 0
	ds_read_b32 v82, v198 offset:24576
	v_mul_f32_e32 v1, 0x3fb8aa3b, v1
	v_exp_f32_e32 v1, v1
	s_waitcnt lgkmcnt(1)
	v_mul_f32_e32 v87, v87, v78
	v_add_f32_e32 v78, -1.0, v78
	v_fma_f32 v78, v176, v78, 1.0
	s_waitcnt lgkmcnt(0)
	v_mul_f32_e32 v78, v82, v78
	ds_write2st64_b32 v198, v78, v1 offset0:96 offset1:128
	v_mul_f32_e32 v1, v86, v78
	v_mul_f32_e32 v78, v177, v1
	ds_write_b32 v198, v87 offset:40960
	s_nop 0
	v_mov_b32_dpp v78, v78 quad_perm:[1,0,3,2] row_mask:0xf bank_mask:0xf bound_ctrl:1
	v_fmac_f32_e32 v78, v177, v1
	s_nop 1
	v_add_f32_dpp v1, v78, v78 quad_perm:[2,3,0,1] row_mask:0xf bank_mask:0xf bound_ctrl:1
	s_nop 1
	v_add_f32_dpp v1, v1, v1 row_half_mirror row_mask:0xf bank_mask:0xf bound_ctrl:1
	s_nop 1
	v_mov_b32_dpp v78, v1 row_mirror row_mask:0xf bank_mask:0xf bound_ctrl:1
	s_and_saveexec_b64 s[6:7], s[40:41]
	v_add_f32_e32 v1, v1, v78
	ds_write_b32 v194, v1 offset:57408
	s_or_b64 exec, exec, s[6:7]
	v_add_f32_e32 v1, v173, v83
	v_mul_f32_e32 v1, 0xbfb8aa3b, v1
	v_exp_f32_e32 v1, v1
	v_add_f32_e32 v78, v175, v79
	v_mul_f32_e32 v78, 0xbfb8aa3b, v78
	v_exp_f32_e32 v78, v78
	v_add_f32_e32 v1, 1.0, v1
	s_nop 3
	v_add_f32_e32 v82, 1.0, v78
	v_rcp_f32_e32 v79, v1
	s_nop 0
	v_mul_f32_e32 v1, s16, v79
	v_mul_f32_e32 v1, 0x3fb8aa3b, v1
	v_exp_f32_e32 v1, v1
	ds_read2st64_b32 v[78:79], v199 offset1:64
	v_rcp_f32_e32 v82, v82
	s_nop 0
	ds_read_b32 v83, v199 offset:24576
	s_waitcnt lgkmcnt(1)
	v_mul_f32_e32 v79, v82, v79
	ds_write_b32 v199, v79 offset:40960
	v_add_f32_e32 v79, -1.0, v82
	v_fma_f32 v79, v176, v79, 1.0
	s_waitcnt lgkmcnt(1)
	v_mul_f32_e32 v79, v79, v83
	ds_write2st64_b32 v199, v79, v1 offset0:96 offset1:128
	v_mul_f32_e32 v1, v79, v78
	v_mul_f32_e32 v78, v177, v1
	s_nop 1
	v_mov_b32_dpp v78, v78 quad_perm:[1,0,3,2] row_mask:0xf bank_mask:0xf bound_ctrl:1
	v_fmac_f32_e32 v78, v177, v1
	s_nop 1
	v_add_f32_dpp v1, v78, v78 quad_perm:[2,3,0,1] row_mask:0xf bank_mask:0xf bound_ctrl:1
	s_nop 1
	v_add_f32_dpp v1, v1, v1 row_half_mirror row_mask:0xf bank_mask:0xf bound_ctrl:1
	s_nop 1
	v_mov_b32_dpp v78, v1 row_mirror row_mask:0xf bank_mask:0xf bound_ctrl:1
	s_and_saveexec_b64 s[6:7], s[40:41]
	v_add_f32_e32 v1, v1, v78
	ds_write_b32 v194, v1 offset:57412
	s_or_b64 exec, exec, s[6:7]
	v_add_f32_e32 v1, v173, v84
	v_mul_f32_e32 v1, 0xbfb8aa3b, v1
	v_exp_f32_e32 v1, v1
	v_add_f32_e32 v78, v175, v80
	v_mul_f32_e32 v78, 0xbfb8aa3b, v78
	v_exp_f32_e32 v78, v78
	v_add_f32_e32 v1, 1.0, v1
	s_nop 3
	v_add_f32_e32 v80, 1.0, v78
	v_rcp_f32_e32 v79, v1
	s_nop 0
	v_mul_f32_e32 v1, s16, v79
	v_mul_f32_e32 v1, 0x3fb8aa3b, v1
	v_exp_f32_e32 v1, v1
	ds_read2st64_b32 v[78:79], v200 offset1:64
	v_rcp_f32_e32 v80, v80
	s_nop 0
	ds_read_b32 v82, v200 offset:24576
	s_waitcnt lgkmcnt(1)
	v_mul_f32_e32 v79, v80, v79
	ds_write_b32 v200, v79 offset:40960
	v_add_f32_e32 v79, -1.0, v80
	v_fma_f32 v79, v176, v79, 1.0
	s_waitcnt lgkmcnt(1)
	v_mul_f32_e32 v79, v79, v82
	ds_write2st64_b32 v200, v79, v1 offset0:96 offset1:128
	v_mul_f32_e32 v1, v79, v78
	v_mul_f32_e32 v78, v177, v1
	s_nop 1
	v_mov_b32_dpp v78, v78 quad_perm:[1,0,3,2] row_mask:0xf bank_mask:0xf bound_ctrl:1
	v_fmac_f32_e32 v78, v177, v1
	s_nop 1
	v_add_f32_dpp v1, v78, v78 quad_perm:[2,3,0,1] row_mask:0xf bank_mask:0xf bound_ctrl:1
	s_nop 1
	v_add_f32_dpp v1, v1, v1 row_half_mirror row_mask:0xf bank_mask:0xf bound_ctrl:1
	s_nop 1
	v_mov_b32_dpp v78, v1 row_mirror row_mask:0xf bank_mask:0xf bound_ctrl:1
	s_and_saveexec_b64 s[6:7], s[40:41]
	v_add_f32_e32 v1, v1, v78
	ds_write_b32 v194, v1 offset:57416
	s_or_b64 exec, exec, s[6:7]
	v_add_f32_e32 v1, v173, v85
	v_mul_f32_e32 v1, 0xbfb8aa3b, v1
	v_exp_f32_e32 v1, v1
	v_add_f32_e32 v78, v175, v81
	v_mul_f32_e32 v78, 0xbfb8aa3b, v78
	v_exp_f32_e32 v78, v78
	v_add_f32_e32 v1, 1.0, v1
	s_nop 3
	v_add_f32_e32 v80, 1.0, v78
	v_rcp_f32_e32 v79, v1
	s_nop 0
	v_mul_f32_e32 v1, s16, v79
	v_mul_f32_e32 v1, 0x3fb8aa3b, v1
	v_exp_f32_e32 v1, v1
	ds_read2st64_b32 v[78:79], v201 offset1:64
	v_rcp_f32_e32 v80, v80
	s_nop 0
	ds_read_b32 v81, v201 offset:24576
	s_waitcnt lgkmcnt(1)
	v_mul_f32_e32 v79, v80, v79
	ds_write_b32 v201, v79 offset:40960
	v_add_f32_e32 v79, -1.0, v80
	v_fma_f32 v79, v176, v79, 1.0
	s_waitcnt lgkmcnt(1)
	v_mul_f32_e32 v79, v79, v81
	ds_write2st64_b32 v201, v79, v1 offset0:96 offset1:128
	v_mul_f32_e32 v1, v79, v78
	v_mul_f32_e32 v78, v177, v1
	s_nop 1
	v_mov_b32_dpp v78, v78 quad_perm:[1,0,3,2] row_mask:0xf bank_mask:0xf bound_ctrl:1
	v_fmac_f32_e32 v78, v177, v1
	s_nop 1
	v_add_f32_dpp v1, v78, v78 quad_perm:[2,3,0,1] row_mask:0xf bank_mask:0xf bound_ctrl:1
	s_nop 1
	v_add_f32_dpp v1, v1, v1 row_half_mirror row_mask:0xf bank_mask:0xf bound_ctrl:1
	s_nop 1
	v_mov_b32_dpp v78, v1 row_mirror row_mask:0xf bank_mask:0xf bound_ctrl:1
	s_and_saveexec_b64 s[6:7], s[40:41]
	v_add_f32_e32 v1, v1, v78
	ds_write_b32 v194, v1 offset:57420
	s_or_b64 exec, exec, s[6:7]
	s_add_i32 s10, s1, 1
	s_cmpk_eq_i32 s1, 0x47
	s_cbranch_scc1 .LBB0_682
	s_add_i32 s11, s1, -7
	s_cmp_gt_u32 s1, 6
	s_cselect_b64 s[6:7], -1, 0
	s_and_b64 s[12:13], s[6:7], exec
	s_cselect_b32 s11, s11, s10
	s_cselect_b32 s12, 0x100, 0
	s_cselect_b32 s13, 63, 7
	s_add_i32 s14, s12, s79
	s_sub_i32 s15, s13, s11
	s_and_b64 s[12:13], s[50:51], exec
	s_cselect_b32 s11, s11, s15
	v_lshl_add_u32 v1, s11, 5, v178
	v_add_u32_e32 v18, s14, v1
	v_mad_i64_i32 v[54:55], s[12:13], v18, s17, v[160:161]
	s_mov_b32 s53, s9
	v_lshl_add_u64 v[56:57], v[54:55], 0, s[52:53]
	global_load_dwordx4 v[18:21], v[56:57], off offset:2880
	v_mov_b32_e32 v28, v0
	v_mov_b32_e32 v29, v0
	v_cmp_lt_i32_e64 s[46:47], 0, v1
	v_mov_b64_e32 v[24:25], v[28:29]
	v_mov_b64_e32 v[22:23], v[28:29]
	s_and_saveexec_b64 s[12:13], s[46:47]
	s_cbranch_execz .LBB0_663
	v_add_co_u32_e32 v22, vcc, 0xfffff000, v56
	s_nop 1
	v_addc_co_u32_e32 v23, vcc, -1, v57, vcc
	global_load_dwordx4 v[22:25], v[22:23], off offset:-3008

.LBB0_843:
	v_mul_f32_e32 v158, 0xbfb8aa3b, v158
	v_mul_f32_e32 v159, 0xbfb8aa3b, v159
	v_exp_f32_e32 v158, v158
	v_exp_f32_e32 v159, v159
	v_mul_f32_e32 v154, 0xbfb8aa3b, v154
	v_mul_f32_e32 v155, 0xbfb8aa3b, v155
	v_exp_f32_e32 v154, v154
	v_pk_add_f32 v[158:159], v[158:159], 1.0 op_sel_hi:[1,0]
	v_exp_f32_e32 v155, v155
	s_nop 1
	v_pk_add_f32 v[154:155], v[154:155], 1.0 op_sel_hi:[1,0]
	v_mul_f32_e32 v150, 0xbfb8aa3b, v150
	v_mul_f32_e32 v151, 0xbfb8aa3b, v151
	v_rcp_f32_e32 v159, v159
	s_nop 0
	s_nop 1
	v_exp_f32_e32 v150, v150
	v_exp_f32_e32 v151, v151
	v_mul_f32_e32 v146, 0xbfb8aa3b, v146
	v_rcp_f32_e32 v158, v158
	s_nop 0
	v_cvt_pk_bf16_f32 v158, v158, v159
	v_mul_f32_e32 v159, 0xbfb8aa3b, v160
	v_exp_f32_e32 v160, v159
	v_mul_f32_e32 v159, 0xbfb8aa3b, v161
	v_exp_f32_e32 v161, v159
	v_pk_add_f32 v[150:151], v[150:151], 1.0 op_sel_hi:[1,0]
	v_mul_f32_e32 v147, 0xbfb8aa3b, v147
	v_exp_f32_e32 v146, v146
	v_pk_add_f32 v[160:161], v[160:161], 1.0 op_sel_hi:[1,0]
	v_exp_f32_e32 v147, v147
	s_nop 1
	v_pk_add_f32 v[146:147], v[146:147], 1.0 op_sel_hi:[1,0]
	v_mul_f32_e32 v142, 0xbfb8aa3b, v142
	v_mul_f32_e32 v143, 0xbfb8aa3b, v143
	v_rcp_f32_e32 v159, v161
	s_nop 0
	s_nop 1
	v_exp_f32_e32 v142, v142
	v_exp_f32_e32 v143, v143
	v_mul_f32_e32 v138, 0xbfb8aa3b, v138
	v_rcp_f32_e32 v160, v160
	s_nop 0
	s_nop 1
	v_pk_add_f32 v[142:143], v[142:143], 1.0 op_sel_hi:[1,0]
	v_mul_f32_e32 v139, 0xbfb8aa3b, v139
	v_exp_f32_e32 v138, v138
	v_rcp_f32_e32 v155, v155
	s_nop 0
	s_nop 1
	v_exp_f32_e32 v139, v139
	v_mul_f32_e32 v134, 0xbfb8aa3b, v134
	v_mul_f32_e32 v135, 0xbfb8aa3b, v135
	v_rcp_f32_e32 v154, v154
	s_nop 0
	v_cvt_pk_bf16_f32 v154, v154, v155
	v_mul_f32_e32 v155, 0xbfb8aa3b, v156
	v_exp_f32_e32 v156, v155
	v_mul_f32_e32 v155, 0xbfb8aa3b, v157
	v_exp_f32_e32 v157, v155
	v_pk_add_f32 v[138:139], v[138:139], 1.0 op_sel_hi:[1,0]
	v_exp_f32_e32 v134, v134
	v_exp_f32_e32 v135, v135
	v_pk_add_f32 v[156:157], v[156:157], 1.0 op_sel_hi:[1,0]
	v_mul_f32_e32 v130, 0xbfb8aa3b, v130
	s_nop 1
	v_pk_add_f32 v[134:135], v[134:135], 1.0 op_sel_hi:[1,0]
	v_mul_f32_e32 v131, 0xbfb8aa3b, v131
	v_exp_f32_e32 v130, v130
	v_rcp_f32_e32 v155, v157
	s_nop 0
	s_nop 1
	v_exp_f32_e32 v131, v131
	v_mul_f32_e32 v126, 0xbfb8aa3b, v126
	v_mul_f32_e32 v127, 0xbfb8aa3b, v127
	v_rcp_f32_e32 v156, v156
	s_nop 0
	s_nop 0
	v_pk_add_f32 v[130:131], v[130:131], 1.0 op_sel_hi:[1,0]
	v_exp_f32_e32 v126, v126
	v_exp_f32_e32 v127, v127
	v_rcp_f32_e32 v151, v151
	s_nop 0
	s_nop 2
	v_pk_add_f32 v[126:127], v[126:127], 1.0 op_sel_hi:[1,0]
	v_mul_f32_e32 v122, 0xbfb8aa3b, v122
	v_mul_f32_e32 v123, 0xbfb8aa3b, v123
	v_rcp_f32_e32 v150, v150
	s_nop 0
	v_cvt_pk_bf16_f32 v150, v150, v151
	v_mul_f32_e32 v151, 0xbfb8aa3b, v152
	v_exp_f32_e32 v152, v151
	v_mul_f32_e32 v151, 0xbfb8aa3b, v153
	v_exp_f32_e32 v153, v151
	v_exp_f32_e32 v122, v122
	v_exp_f32_e32 v123, v123
	v_mul_f32_e32 v118, 0xbfb8aa3b, v118
	v_pk_add_f32 v[152:153], v[152:153], 1.0 op_sel_hi:[1,0]
	v_mul_f32_e32 v119, 0xbfb8aa3b, v119
	s_nop 1
	v_pk_add_f32 v[122:123], v[122:123], 1.0 op_sel_hi:[1,0]
	v_exp_f32_e32 v118, v118
	v_exp_f32_e32 v119, v119
	v_rcp_f32_e32 v151, v153
	s_nop 0
	s_nop 2
	v_pk_add_f32 v[118:119], v[118:119], 1.0 op_sel_hi:[1,0]
	v_mul_f32_e32 v114, 0xbfb8aa3b, v114
	v_mul_f32_e32 v115, 0xbfb8aa3b, v115
	v_rcp_f32_e32 v152, v152
	s_nop 0
	s_nop 1
	v_exp_f32_e32 v114, v114
	v_exp_f32_e32 v115, v115
	v_mul_f32_e32 v110, 0xbfb8aa3b, v110
	v_rcp_f32_e32 v147, v147
	s_nop 0
	s_nop 1
	v_pk_add_f32 v[114:115], v[114:115], 1.0 op_sel_hi:[1,0]
	v_mul_f32_e32 v111, 0xbfb8aa3b, v111
	v_exp_f32_e32 v110, v110
	v_rcp_f32_e32 v146, v146
	s_nop 0
	v_cvt_pk_bf16_f32 v146, v146, v147
	v_mul_f32_e32 v147, 0xbfb8aa3b, v148
	v_exp_f32_e32 v148, v147
	v_mul_f32_e32 v147, 0xbfb8aa3b, v149
	v_exp_f32_e32 v149, v147
	v_exp_f32_e32 v111, v111
	v_mul_f32_e32 v102, 0xbfb8aa3b, v102
	v_mul_f32_e32 v103, 0xbfb8aa3b, v103
	v_pk_add_f32 v[148:149], v[148:149], 1.0 op_sel_hi:[1,0]
	v_pk_add_f32 v[110:111], v[110:111], 1.0 op_sel_hi:[1,0]
	s_nop 1
	v_exp_f32_e32 v102, v102
	v_exp_f32_e32 v103, v103
	v_mul_f32_e32 v66, 0xbfb8aa3b, v66
	v_rcp_f32_e32 v147, v149
	s_nop 0
	s_nop 1
	v_pk_add_f32 v[102:103], v[102:103], 1.0 op_sel_hi:[1,0]
	v_mul_f32_e32 v67, 0xbfb8aa3b, v67
	v_exp_f32_e32 v66, v66
	v_rcp_f32_e32 v148, v148
	s_nop 0
	s_nop 1
	v_exp_f32_e32 v67, v67
	v_mul_f32_e32 v34, 0xbfb8aa3b, v34
	v_mul_f32_e32 v35, 0xbfb8aa3b, v35
	v_rcp_f32_e32 v143, v143
	s_nop 0
	s_nop 0
	v_pk_add_f32 v[66:67], v[66:67], 1.0 op_sel_hi:[1,0]
	v_exp_f32_e32 v34, v34
	v_exp_f32_e32 v35, v35
	v_rcp_f32_e32 v142, v142
	s_nop 0
	v_cvt_pk_bf16_f32 v142, v142, v143
	v_mul_f32_e32 v143, 0xbfb8aa3b, v144
	v_exp_f32_e32 v144, v143
	v_mul_f32_e32 v143, 0xbfb8aa3b, v145
	v_exp_f32_e32 v145, v143
	v_pk_add_f32 v[34:35], v[34:35], 1.0 op_sel_hi:[1,0]
	s_waitcnt lgkmcnt(0)
	s_add_i32 s8, s8, 1
	v_pk_add_f32 v[144:145], v[144:145], 1.0 op_sel_hi:[1,0]
	s_addk_i32 s44, 0x400
	s_nop 1
	s_cmp_eq_u32 s8, 4
	s_barrier
	v_rcp_f32_e32 v143, v145
	s_nop 0
	s_nop 0
	v_rcp_f32_e32 v144, v144
	s_nop 0
	s_nop 0
	v_rcp_f32_e32 v139, v139
	s_nop 0
	s_nop 0
	v_rcp_f32_e32 v138, v138
	s_nop 0
	v_cvt_pk_bf16_f32 v138, v138, v139
	v_mul_f32_e32 v139, 0xbfb8aa3b, v140
	v_exp_f32_e32 v140, v139
	v_mul_f32_e32 v139, 0xbfb8aa3b, v141
	v_exp_f32_e32 v141, v139
	s_nop 0
	v_pk_add_f32 v[140:141], v[140:141], 1.0 op_sel_hi:[1,0]
	s_nop 0
	s_nop 0
	v_rcp_f32_e32 v139, v141
	s_nop 0
	s_nop 0
	v_rcp_f32_e32 v140, v140
	s_nop 0
	s_nop 0
	v_rcp_f32_e32 v135, v135
	s_nop 0
	s_nop 0
	v_rcp_f32_e32 v134, v134
	s_nop 0
	v_cvt_pk_bf16_f32 v134, v134, v135
	v_mul_f32_e32 v135, 0xbfb8aa3b, v136
	v_exp_f32_e32 v136, v135
	v_mul_f32_e32 v135, 0xbfb8aa3b, v137
	v_exp_f32_e32 v137, v135
	s_nop 0
	v_pk_add_f32 v[136:137], v[136:137], 1.0 op_sel_hi:[1,0]
	s_nop 0
	s_nop 0
	v_rcp_f32_e32 v135, v137
	s_nop 0
	s_nop 0
	v_rcp_f32_e32 v136, v136
	s_nop 0
	s_nop 0
	v_rcp_f32_e32 v131, v131
	s_nop 0
	s_nop 0
	v_rcp_f32_e32 v130, v130
	s_nop 0
	v_cvt_pk_bf16_f32 v130, v130, v131
	v_mul_f32_e32 v131, 0xbfb8aa3b, v132
	v_exp_f32_e32 v132, v131
	v_mul_f32_e32 v131, 0xbfb8aa3b, v133
	v_exp_f32_e32 v133, v131
	s_nop 0
	v_pk_add_f32 v[132:133], v[132:133], 1.0 op_sel_hi:[1,0]
	s_nop 0
	s_nop 0
	v_rcp_f32_e32 v131, v133
	s_nop 0
	s_nop 0
	v_rcp_f32_e32 v132, v132
	s_nop 0
	v_cvt_pk_bf16_f32 v131, v132, v131
	v_rcp_f32_e32 v127, v127
	s_nop 0
	s_nop 0
	v_rcp_f32_e32 v126, v126
	s_nop 0
	v_cvt_pk_bf16_f32 v126, v126, v127
	v_mul_f32_e32 v127, 0xbfb8aa3b, v128
	v_exp_f32_e32 v128, v127
	v_mul_f32_e32 v127, 0xbfb8aa3b, v129
	v_exp_f32_e32 v129, v127
	s_nop 0
	v_pk_add_f32 v[128:129], v[128:129], 1.0 op_sel_hi:[1,0]
	s_nop 0
	s_nop 0
	v_rcp_f32_e32 v127, v129
	s_nop 0
	s_nop 0
	v_rcp_f32_e32 v128, v128
	s_nop 0
	v_cvt_pk_bf16_f32 v127, v128, v127
	v_rcp_f32_e32 v123, v123
	s_nop 0
	s_nop 0
	v_rcp_f32_e32 v122, v122
	s_nop 0
	v_cvt_pk_bf16_f32 v122, v122, v123
	v_mul_f32_e32 v123, 0xbfb8aa3b, v124
	v_exp_f32_e32 v124, v123
	v_mul_f32_e32 v123, 0xbfb8aa3b, v125
	v_exp_f32_e32 v125, v123
	s_nop 0
	v_pk_add_f32 v[124:125], v[124:125], 1.0 op_sel_hi:[1,0]
	s_nop 0
	s_nop 0
	v_rcp_f32_e32 v123, v125
	s_nop 0
	s_nop 0
	v_rcp_f32_e32 v124, v124
	s_nop 0
	v_cvt_pk_bf16_f32 v123, v124, v123
	v_rcp_f32_e32 v119, v119
	s_nop 0
	s_nop 0
	v_rcp_f32_e32 v118, v118
	s_nop 0
	v_cvt_pk_bf16_f32 v118, v118, v119
	v_mul_f32_e32 v119, 0xbfb8aa3b, v120
	v_exp_f32_e32 v120, v119
	v_mul_f32_e32 v119, 0xbfb8aa3b, v121
	v_exp_f32_e32 v121, v119
	s_nop 0
	v_pk_add_f32 v[120:121], v[120:121], 1.0 op_sel_hi:[1,0]
	s_nop 0
	s_nop 0
	v_rcp_f32_e32 v119, v121
	s_nop 0
	s_nop 0
	v_rcp_f32_e32 v120, v120
	s_nop 0
	v_cvt_pk_bf16_f32 v119, v120, v119
	v_rcp_f32_e32 v115, v115
	s_nop 0
	s_nop 0
	v_rcp_f32_e32 v114, v114
	s_nop 0
	v_cvt_pk_bf16_f32 v114, v114, v115
	v_mul_f32_e32 v115, 0xbfb8aa3b, v116
	v_exp_f32_e32 v116, v115
	v_mul_f32_e32 v115, 0xbfb8aa3b, v117
	v_exp_f32_e32 v117, v115
	s_nop 0
	v_pk_add_f32 v[116:117], v[116:117], 1.0 op_sel_hi:[1,0]
	s_nop 0
	s_nop 0
	v_rcp_f32_e32 v115, v117
	s_nop 0
	s_nop 0
	v_rcp_f32_e32 v116, v116
	s_nop 0
	v_cvt_pk_bf16_f32 v115, v116, v115
	v_rcp_f32_e32 v111, v111
	s_nop 0
	s_nop 0
	v_rcp_f32_e32 v110, v110
	s_nop 0
	v_cvt_pk_bf16_f32 v110, v110, v111
	v_mul_f32_e32 v111, 0xbfb8aa3b, v112
	v_exp_f32_e32 v112, v111
	v_mul_f32_e32 v111, 0xbfb8aa3b, v113
	v_exp_f32_e32 v113, v111
	v_cvt_pk_bf16_f32 v133, v136, v135
	v_pk_add_f32 v[112:113], v[112:113], 1.0 op_sel_hi:[1,0]
	s_nop 0
	s_nop 0
	v_rcp_f32_e32 v111, v113
	s_nop 0
	s_nop 0
	v_rcp_f32_e32 v112, v112
	s_nop 0
	v_cvt_pk_bf16_f32 v111, v112, v111
	v_rcp_f32_e32 v103, v103
	s_nop 0
	s_nop 0
	v_rcp_f32_e32 v102, v102
	s_nop 0
	v_cvt_pk_bf16_f32 v102, v102, v103
	v_mul_f32_e32 v103, 0xbfb8aa3b, v104
	v_exp_f32_e32 v104, v103
	v_mul_f32_e32 v103, 0xbfb8aa3b, v105
	v_exp_f32_e32 v105, v103
	v_cvt_pk_bf16_f32 v129, v140, v139
	v_pk_add_f32 v[104:105], v[104:105], 1.0 op_sel_hi:[1,0]
	s_nop 0
	s_nop 0
	v_rcp_f32_e32 v103, v105
	s_nop 0
	s_nop 0
	v_rcp_f32_e32 v104, v104
	s_nop 0
	v_cvt_pk_bf16_f32 v103, v104, v103
	v_rcp_f32_e32 v67, v67
	s_nop 0
	s_nop 0
	v_rcp_f32_e32 v66, v66
	s_nop 0
	v_cvt_pk_bf16_f32 v66, v66, v67
	v_mul_f32_e32 v67, 0xbfb8aa3b, v68
	v_exp_f32_e32 v68, v67
	v_mul_f32_e32 v67, 0xbfb8aa3b, v69
	v_exp_f32_e32 v69, v67
	v_cvt_pk_bf16_f32 v125, v144, v143
	v_pk_add_f32 v[68:69], v[68:69], 1.0 op_sel_hi:[1,0]
	s_nop 0
	s_nop 0
	v_rcp_f32_e32 v67, v69
	s_nop 0
	s_nop 0
	v_rcp_f32_e32 v68, v68
	s_nop 0
	v_cvt_pk_bf16_f32 v67, v68, v67
	v_rcp_f32_e32 v35, v35
	s_nop 0
	s_nop 0
	v_rcp_f32_e32 v34, v34
	s_nop 0
	v_cvt_pk_bf16_f32 v69, v34, v35
	v_mul_f32_e32 v34, 0xbfb8aa3b, v36
	v_mul_f32_e32 v35, 0xbfb8aa3b, v37
	v_exp_f32_e32 v34, v34
	v_exp_f32_e32 v35, v35
	v_cvt_pk_bf16_f32 v121, v148, v147
	v_pk_add_f32 v[34:35], v[34:35], 1.0 op_sel_hi:[1,0]
	s_nop 0
	s_nop 0
	v_rcp_f32_e32 v35, v35
	s_nop 0
	s_nop 0
	v_rcp_f32_e32 v34, v34
	s_nop 0
	v_cvt_pk_bf16_f32 v105, v160, v159
	v_cvt_pk_bf16_f32 v68, v34, v35
	v_lshlrev_b32_e32 v34, 16, v26
	v_lshlrev_b32_e32 v36, 16, v158
	v_and_b32_e32 v35, 0xffff0000, v26
	v_and_b32_e32 v37, 0xffff0000, v158
	v_pk_fma_f32 v[34:35], v[106:107], v[36:37], v[34:35]
	v_lshlrev_b32_e32 v26, 16, v27
	v_lshlrev_b32_e32 v36, 16, v105
	v_and_b32_e32 v27, 0xffff0000, v27
	v_and_b32_e32 v37, 0xffff0000, v105
	v_pk_fma_f32 v[36:37], v[108:109], v[36:37], v[26:27]
	v_cvt_pk_bf16_f32 v113, v156, v155
	v_cvt_pk_bf16_f32 v26, v34, v35
	v_cvt_pk_bf16_f32 v27, v36, v37
	v_lshlrev_b32_e32 v34, 16, v28
	v_lshlrev_b32_e32 v36, 16, v154
	v_and_b32_e32 v35, 0xffff0000, v28
	v_and_b32_e32 v37, 0xffff0000, v154
	v_pk_fma_f32 v[34:35], v[98:99], v[36:37], v[34:35]
	v_lshlrev_b32_e32 v28, 16, v29
	v_lshlrev_b32_e32 v36, 16, v113
	v_and_b32_e32 v29, 0xffff0000, v29
	v_and_b32_e32 v37, 0xffff0000, v113
	v_pk_fma_f32 v[36:37], v[100:101], v[36:37], v[28:29]
	v_cvt_pk_bf16_f32 v117, v152, v151
	v_cvt_pk_bf16_f32 v28, v34, v35
	v_cvt_pk_bf16_f32 v29, v36, v37
	v_lshlrev_b32_e32 v34, 16, v30
	v_lshlrev_b32_e32 v36, 16, v150
	v_and_b32_e32 v35, 0xffff0000, v30
	v_and_b32_e32 v37, 0xffff0000, v150
	v_pk_fma_f32 v[34:35], v[94:95], v[36:37], v[34:35]
	v_lshlrev_b32_e32 v30, 16, v31
	v_lshlrev_b32_e32 v36, 16, v117
	v_and_b32_e32 v31, 0xffff0000, v31
	v_and_b32_e32 v37, 0xffff0000, v117
	v_pk_fma_f32 v[36:37], v[96:97], v[36:37], v[30:31]
	v_cvt_pk_bf16_f32 v30, v34, v35
	v_cvt_pk_bf16_f32 v31, v36, v37
	v_lshlrev_b32_e32 v34, 16, v32
	v_lshlrev_b32_e32 v36, 16, v146
	v_and_b32_e32 v35, 0xffff0000, v32
	v_and_b32_e32 v37, 0xffff0000, v146
	v_pk_fma_f32 v[34:35], v[90:91], v[36:37], v[34:35]
	v_lshlrev_b32_e32 v32, 16, v33
	v_lshlrev_b32_e32 v36, 16, v121
	v_and_b32_e32 v33, 0xffff0000, v33
	v_and_b32_e32 v37, 0xffff0000, v121
	v_pk_fma_f32 v[36:37], v[92:93], v[36:37], v[32:33]
	v_cvt_pk_bf16_f32 v32, v34, v35
	v_cvt_pk_bf16_f32 v33, v36, v37
	v_lshlrev_b32_e32 v34, 16, v22
	v_lshlrev_b32_e32 v36, 16, v142
	v_and_b32_e32 v35, 0xffff0000, v22
	v_and_b32_e32 v37, 0xffff0000, v142
	v_pk_fma_f32 v[34:35], v[86:87], v[36:37], v[34:35]
	v_lshlrev_b32_e32 v22, 16, v23
	v_lshlrev_b32_e32 v36, 16, v125
	v_and_b32_e32 v23, 0xffff0000, v23
	v_and_b32_e32 v37, 0xffff0000, v125
	v_pk_fma_f32 v[36:37], v[88:89], v[36:37], v[22:23]
	v_cvt_pk_bf16_f32 v22, v34, v35
	v_cvt_pk_bf16_f32 v23, v36, v37
	v_lshlrev_b32_e32 v34, 16, v24
	v_lshlrev_b32_e32 v36, 16, v138
	v_and_b32_e32 v35, 0xffff0000, v24
	v_and_b32_e32 v37, 0xffff0000, v138
	v_pk_fma_f32 v[34:35], v[82:83], v[36:37], v[34:35]
	v_lshlrev_b32_e32 v24, 16, v25
	v_lshlrev_b32_e32 v36, 16, v129
	v_and_b32_e32 v25, 0xffff0000, v25
	v_and_b32_e32 v37, 0xffff0000, v129
	v_pk_fma_f32 v[36:37], v[84:85], v[36:37], v[24:25]
	v_cvt_pk_bf16_f32 v24, v34, v35
	v_cvt_pk_bf16_f32 v25, v36, v37
	v_lshlrev_b32_e32 v34, 16, v18
	v_lshlrev_b32_e32 v36, 16, v134
	v_and_b32_e32 v35, 0xffff0000, v18
	v_and_b32_e32 v37, 0xffff0000, v134
	v_pk_fma_f32 v[34:35], v[78:79], v[36:37], v[34:35]
	v_lshlrev_b32_e32 v18, 16, v19
	v_lshlrev_b32_e32 v36, 16, v133
	v_and_b32_e32 v19, 0xffff0000, v19
	v_and_b32_e32 v37, 0xffff0000, v133
	v_pk_fma_f32 v[36:37], v[80:81], v[36:37], v[18:19]
	v_cvt_pk_bf16_f32 v18, v34, v35
	v_cvt_pk_bf16_f32 v19, v36, v37
	v_lshlrev_b32_e32 v34, 16, v20
	v_lshlrev_b32_e32 v36, 16, v130
	v_and_b32_e32 v35, 0xffff0000, v20
	v_and_b32_e32 v37, 0xffff0000, v130
	v_pk_fma_f32 v[34:35], v[74:75], v[36:37], v[34:35]
	v_lshlrev_b32_e32 v20, 16, v21
	v_lshlrev_b32_e32 v36, 16, v131
	v_and_b32_e32 v21, 0xffff0000, v21
	v_and_b32_e32 v37, 0xffff0000, v131
	v_pk_fma_f32 v[36:37], v[76:77], v[36:37], v[20:21]
	v_cvt_pk_bf16_f32 v20, v34, v35
	v_cvt_pk_bf16_f32 v21, v36, v37
	v_lshlrev_b32_e32 v34, 16, v14
	v_lshlrev_b32_e32 v36, 16, v126
	v_and_b32_e32 v35, 0xffff0000, v14
	v_and_b32_e32 v37, 0xffff0000, v126
	v_pk_fma_f32 v[34:35], v[70:71], v[36:37], v[34:35]
	v_lshlrev_b32_e32 v14, 16, v15
	v_lshlrev_b32_e32 v36, 16, v127
	v_and_b32_e32 v15, 0xffff0000, v15
	v_and_b32_e32 v37, 0xffff0000, v127
	v_pk_fma_f32 v[36:37], v[72:73], v[36:37], v[14:15]
	v_cvt_pk_bf16_f32 v14, v34, v35
	v_cvt_pk_bf16_f32 v15, v36, v37
	v_lshlrev_b32_e32 v34, 16, v16
	v_lshlrev_b32_e32 v36, 16, v122
	v_and_b32_e32 v35, 0xffff0000, v16
	v_and_b32_e32 v37, 0xffff0000, v122
	v_pk_fma_f32 v[34:35], v[62:63], v[36:37], v[34:35]
	v_lshlrev_b32_e32 v16, 16, v17
	v_lshlrev_b32_e32 v36, 16, v123
	v_and_b32_e32 v17, 0xffff0000, v17
	v_and_b32_e32 v37, 0xffff0000, v123
	v_pk_fma_f32 v[36:37], v[64:65], v[36:37], v[16:17]
	v_cvt_pk_bf16_f32 v16, v34, v35
	v_cvt_pk_bf16_f32 v17, v36, v37
	v_lshlrev_b32_e32 v34, 16, v10
	v_lshlrev_b32_e32 v36, 16, v118
	v_and_b32_e32 v35, 0xffff0000, v10
	v_and_b32_e32 v37, 0xffff0000, v118
	v_pk_fma_f32 v[34:35], v[58:59], v[36:37], v[34:35]
	v_lshlrev_b32_e32 v10, 16, v11
	v_lshlrev_b32_e32 v36, 16, v119
	v_and_b32_e32 v11, 0xffff0000, v11
	v_and_b32_e32 v37, 0xffff0000, v119
	v_pk_fma_f32 v[36:37], v[60:61], v[36:37], v[10:11]
	v_cvt_pk_bf16_f32 v10, v34, v35
	v_cvt_pk_bf16_f32 v11, v36, v37
	v_lshlrev_b32_e32 v34, 16, v12
	v_lshlrev_b32_e32 v36, 16, v114
	v_and_b32_e32 v35, 0xffff0000, v12
	v_and_b32_e32 v37, 0xffff0000, v114
	v_pk_fma_f32 v[34:35], v[54:55], v[36:37], v[34:35]
	v_lshlrev_b32_e32 v12, 16, v13
	v_lshlrev_b32_e32 v36, 16, v115
	v_and_b32_e32 v13, 0xffff0000, v13
	v_and_b32_e32 v37, 0xffff0000, v115
	v_pk_fma_f32 v[36:37], v[56:57], v[36:37], v[12:13]
	v_cvt_pk_bf16_f32 v12, v34, v35
	v_cvt_pk_bf16_f32 v13, v36, v37
	v_lshlrev_b32_e32 v34, 16, v6
	v_lshlrev_b32_e32 v36, 16, v110
	v_and_b32_e32 v35, 0xffff0000, v6
	v_and_b32_e32 v37, 0xffff0000, v110
	v_pk_fma_f32 v[34:35], v[50:51], v[36:37], v[34:35]
	v_lshlrev_b32_e32 v6, 16, v7
	v_lshlrev_b32_e32 v36, 16, v111
	v_and_b32_e32 v7, 0xffff0000, v7
	v_and_b32_e32 v37, 0xffff0000, v111
	v_pk_fma_f32 v[36:37], v[52:53], v[36:37], v[6:7]
	v_cvt_pk_bf16_f32 v6, v34, v35
	v_cvt_pk_bf16_f32 v7, v36, v37
	v_lshlrev_b32_e32 v34, 16, v8
	v_lshlrev_b32_e32 v36, 16, v102
	v_and_b32_e32 v35, 0xffff0000, v8
	v_and_b32_e32 v37, 0xffff0000, v102
	v_pk_fma_f32 v[34:35], v[46:47], v[36:37], v[34:35]
	v_lshlrev_b32_e32 v8, 16, v9
	v_lshlrev_b32_e32 v36, 16, v103
	v_and_b32_e32 v9, 0xffff0000, v9
	v_and_b32_e32 v37, 0xffff0000, v103
	v_pk_fma_f32 v[36:37], v[48:49], v[36:37], v[8:9]
	v_cvt_pk_bf16_f32 v8, v34, v35
	v_cvt_pk_bf16_f32 v9, v36, v37
	v_lshlrev_b32_e32 v34, 16, v2
	v_lshlrev_b32_e32 v36, 16, v66
	v_and_b32_e32 v35, 0xffff0000, v2
	v_and_b32_e32 v37, 0xffff0000, v66
	v_pk_fma_f32 v[34:35], v[42:43], v[36:37], v[34:35]
	v_lshlrev_b32_e32 v2, 16, v3
	v_lshlrev_b32_e32 v36, 16, v67
	v_and_b32_e32 v3, 0xffff0000, v3
	v_and_b32_e32 v37, 0xffff0000, v67
	v_pk_fma_f32 v[36:37], v[44:45], v[36:37], v[2:3]
	v_cvt_pk_bf16_f32 v2, v34, v35
	v_cvt_pk_bf16_f32 v3, v36, v37
	v_lshlrev_b32_e32 v34, 16, v4
	v_lshlrev_b32_e32 v36, 16, v69
	v_and_b32_e32 v35, 0xffff0000, v4
	v_and_b32_e32 v37, 0xffff0000, v69
	v_pk_fma_f32 v[34:35], v[38:39], v[36:37], v[34:35]
	v_lshlrev_b32_e32 v4, 16, v5
	v_lshlrev_b32_e32 v36, 16, v68
	v_and_b32_e32 v5, 0xffff0000, v5
	v_and_b32_e32 v37, 0xffff0000, v68
	v_pk_fma_f32 v[36:37], v[40:41], v[36:37], v[4:5]
	v_cvt_pk_bf16_f32 v4, v34, v35
	v_cvt_pk_bf16_f32 v5, v36, v37
	s_cbranch_scc1 .LBB0_836
